# XCD-aware item mapping for MLA and natten items (id bit fields 0-2 and 3-5 swapped so blocks sharing K/V sit on one XCD) on top of natten bias C-init
# speedup vs baseline: 1.0059x; 1.0059x over previous
.LBB0_334:
	s_and_b64 vcc, exec, s[0:1]
	s_cbranch_vccz .LBB0_321
	v_writelane_b32 v253, s3, 44
	s_bfe_u32 s0, s2, 0x10006
	s_and_b32 s3, s2, 7
	s_lshl_b32 s0, s0, 3
	s_or_b32 s0, s0, s3
	v_writelane_b32 v253, s0, 45
	s_bfe_u32 s0, s2, 0x30003
	v_mov_b32_e32 v2, v193
	s_lshl_b32 s0, s0, 2
	v_sub_u32_e64 v0, s0, 1 clamp
	v_ashrrev_i32_e32 v6, 6, v2
	v_writelane_b32 v253, s2, 46
	v_add_u32_e32 v7, s0, v6
	s_max_u32 s2, s0, 4
	v_readfirstlane_b32 s0, v0
	s_min_u32 s3, s0, 24
	s_movk_i32 s0, 0x1d1
	v_cmp_gt_i32_e32 vcc, s0, v2
	s_barrier
	s_and_saveexec_b64 s[0:1], vcc
	s_cbranch_execz .LBB0_343
	v_max_i32_e32 v0, 0xd1, v2
	v_sub_u32_e32 v0, v0, v2
	v_add_u32_e32 v0, 0xff, v0
	s_movk_i32 s4, 0xff
	v_cmp_lt_u32_e32 vcc, s4, v0
	s_mov_b64 s[6:7], -1
	v_mov_b32_e32 v4, v2
	s_and_saveexec_b64 s[4:5], vcc
	s_cbranch_execz .LBB0_340
	v_readlane_b32 s6, v253, 43
	v_readlane_b32 s7, v253, 45
	s_or_b32 s6, s7, s6
	v_readlane_b32 s8, v253, 12
	v_lshrrev_b32_e32 v0, 8, v0
	s_mulk_i32 s6, 0x744
	v_readlane_b32 s18, v253, 22
	v_add_u32_e32 v0, 1, v0
	v_readlane_b32 s9, v253, 13
	v_readlane_b32 s19, v253, 23
	s_add_u32 s6, s18, s6
	v_and_b32_e32 v8, 0x1fffffe, v0
	v_add_u32_e32 v3, 0x100, v2
	v_readlane_b32 s8, v255, 34
	s_addc_u32 s7, s19, 0
	v_mov_b32_e32 v10, v8
	v_lshl_add_u32 v9, v2, 2, s8
	s_mov_b64 s[8:9], 0
	v_mov_b64_e32 v[4:5], v[2:3]
	v_readlane_b32 s10, v253, 14
	v_readlane_b32 s11, v253, 15
	v_readlane_b32 s12, v253, 16
	v_readlane_b32 s13, v253, 17
	v_readlane_b32 s14, v253, 18
	v_readlane_b32 s15, v253, 19
	v_readlane_b32 s16, v253, 20
	v_readlane_b32 s17, v253, 21
	v_readlane_b32 s20, v253, 24
	v_readlane_b32 s21, v253, 25
	v_readlane_b32 s22, v253, 26
	v_readlane_b32 s23, v253, 27

.LBB0_345:
	s_andn2_b64 vcc, exec, s[0:1]
	s_cbranch_vccnz .LBB0_449
	v_max_i32_e32 v0, 4, v7
	v_sub_u32_e64 v7, v3, 8 clamp
	v_sub_u32_e32 v7, v191, v7
	v_add_u32_e32 v8, 1, v7
	v_cmp_gt_u32_e64 s[4:5], 16, v8
	v_add_u32_e32 v8, 2, v7
	v_cmp_gt_u32_e64 s[6:7], 16, v8
	v_add_u32_e32 v8, 3, v7
	v_cmp_gt_u32_e64 s[8:9], 16, v8
	v_add_u32_e32 v8, 8, v7
	v_cmp_gt_u32_e64 s[10:11], 16, v8
	v_add_u32_e32 v8, 9, v7
	v_cmp_gt_u32_e64 s[12:13], 16, v8
	v_add_u32_e32 v8, 10, v7
	v_cmp_gt_u32_e64 s[14:15], 16, v8
	v_add_u32_e32 v8, 11, v7
	v_cmp_gt_u32_e64 s[16:17], 16, v8
	v_add_u32_e32 v8, 17, v7
	v_cmp_gt_u32_e64 s[20:21], 16, v8
	v_add_u32_e32 v8, 18, v7
	s_bfe_u32 s0, s25, 0x30005
	v_cmp_gt_u32_e64 s[22:23], 16, v8
	v_add_u32_e32 v8, 19, v7
	v_writelane_b32 v253, s25, 47
	s_lshl_b32 s1, s0, 2
	v_cmp_gt_u32_e64 s[24:25], 16, v8
	v_add_u32_e32 v8, 24, v7
	v_sub_u32_e64 v5, s1, 1 clamp
	v_cmp_gt_u32_e64 s[26:27], 16, v8
	v_add_u32_e32 v8, 25, v7
	s_max_u32 s3, s1, 4
	v_sub_u32_e64 v195, s1, 4 clamp
	v_readfirstlane_b32 s1, v5
	v_cmp_gt_u32_e64 s[28:29], 16, v8
	v_add_u32_e32 v8, 26, v7
	s_min_u32 s1, s1, 24
	v_cmp_gt_u32_e64 s[30:31], 16, v8
	v_add_u32_e32 v8, 27, v7
	s_mul_i32 s83, s0, 0x1f0
	s_lshl_b32 s0, s3, 6
	s_lshl_b32 s1, s1, 6
	v_cmp_gt_u32_e64 s[34:35], 16, v8
	v_and_b32_e32 v8, -16, v7
	s_mul_i32 s82, s3, 0x7c
	s_sub_i32 s0, s0, s1
	s_movk_i32 s3, 0xffef
	v_cmp_eq_u32_e64 s[36:37], s51, v8
	v_add_u32_e32 v8, 33, v7
	s_add_i32 s84, s0, 0x580
	v_cmp_gt_u32_e64 s[0:1], 16, v7
	v_cmp_lt_u32_e64 s[18:19], s3, v7
	v_cmp_gt_u32_e64 s[38:39], 16, v8
	v_add_u32_e32 v8, 34, v7
	v_add_u32_e32 v7, 35, v7
	v_cmp_gt_u32_e64 s[42:43], 16, v7
	v_min_u32_e32 v7, 24, v3
	v_sub_u32_e32 v7, v191, v7
	v_add_u32_e32 v9, 1, v7
	v_cmp_gt_u32_e64 s[40:41], 16, v8
	v_subrev_u32_e32 v8, 24, v7
	v_cmp_gt_u32_e64 s[46:47], 16, v9
	v_add_u32_e32 v9, 2, v7
	v_cmp_gt_u32_e64 s[48:49], 16, v9
	v_add_u32_e32 v9, 3, v7
	s_movk_i32 s76, 0xffe0
	v_and_b32_e32 v8, -16, v8
	v_cmp_lt_u32_e64 s[60:61], s3, v7
	s_movk_i32 s3, 0xffd0
	v_cmp_gt_u32_e64 s[50:51], 16, v9
	v_cmp_eq_u32_e64 s[52:53], s76, v8
	v_add_u32_e32 v9, 9, v7
	v_cmp_eq_u32_e64 s[68:69], s3, v8
	v_add_u32_e32 v8, 25, v7
	v_add_u32_e32 v0, -4, v0
	v_cmp_gt_u32_e64 s[54:55], 16, v9
	v_add_u32_e32 v9, 10, v7
	v_cmp_gt_u32_e64 s[70:71], 16, v8
	v_add_u32_e32 v8, 26, v7
	v_min_u32_e32 v194, 24, v0
	v_lshlrev_b32_e32 v0, 3, v2
	v_mul_u32_u24_e32 v5, 0x48, v3
	v_cmp_gt_u32_e64 s[56:57], 16, v9
	v_add_u32_e32 v9, 11, v7
	v_cmp_gt_u32_e64 s[72:73], 16, v8
	v_add_u32_e32 v8, 27, v7
	v_lshl_add_u32 v2, v2, 4, s82
	v_lshlrev_b32_e32 v3, 2, v3
	s_movk_i32 s3, 0x7c
	v_cmp_gt_u32_e64 s[58:59], 16, v9
	v_add_u32_e32 v9, 17, v7
	v_cmp_gt_u32_e64 s[74:75], 16, v8
	v_and_b32_e32 v8, -16, v7
	v_sub_u32_e32 v2, v2, v3
	v_mul_lo_u32 v3, v6, s3
	v_lshlrev_b32_e32 v4, 1, v0
	v_cmp_gt_u32_e64 s[62:63], 16, v9
	v_add_u32_e32 v9, 18, v7
	v_cmp_eq_u32_e64 s[76:77], s76, v8
	v_add_u32_e32 v8, 33, v7
	v_sub_u32_e32 v2, v2, v3
	v_lshlrev_b32_e32 v3, 1, v5
	v_cmp_gt_u32_e64 s[44:45], 16, v7
	v_cmp_gt_u32_e64 s[64:65], 16, v9
	v_add_u32_e32 v9, 19, v7
	v_cmp_gt_u32_e64 s[78:79], 16, v8
	v_add_u32_e32 v8, 34, v7
	v_add_u32_e32 v7, 35, v7
	v_subrev_u32_e32 v2, s83, v2
	v_add3_u32 v215, 0, v4, v3
	v_readlane_b32 s3, v255, 35
	v_mov_b32_e32 v14, v1
	v_mov_b32_e32 v15, v1
	v_cmp_gt_u32_e64 s[66:67], 16, v9
	v_cmp_gt_u32_e64 s[80:81], 16, v8
	v_cmp_gt_u32_e64 s[82:83], 16, v7
	v_sub_u32_e32 v216, v215, v0
	v_add3_u32 v217, 0, v0, v3
	v_add_u32_e32 v218, s3, v2
	v_mov_b32_e32 v0, v1
	v_mov_b32_e32 v2, v1
	v_mov_b32_e32 v3, v1
	v_mov_b32_e32 v4, v1
	v_mov_b32_e32 v5, v1
	v_mov_b32_e32 v6, v1
	v_mov_b32_e32 v7, v1
	v_mov_b32_e32 v8, v1
	v_mov_b32_e32 v9, v1
	v_mov_b32_e32 v10, v1
	v_mov_b32_e32 v11, v1
	v_mov_b32_e32 v12, v1
	v_mov_b32_e32 v13, v1
	v_mov_b64_e32 v[80:81], v[14:15]
	v_mov_b64_e32 v[96:97], v[14:15]
	v_mov_b64_e32 v[112:113], v[14:15]
	v_mov_b64_e32 v[128:129], v[14:15]
	s_add_i32 s2, s2, 16
	v_add_u32_e32 v214, 8, v194
	v_mov_b32_e32 v163, 0xf149f2ca
	v_mov_b32_e32 v219, 0
	v_mov_b64_e32 v[78:79], v[12:13]
	v_mov_b64_e32 v[76:77], v[10:11]
	v_mov_b64_e32 v[74:75], v[8:9]
	v_mov_b64_e32 v[72:73], v[6:7]
	v_mov_b64_e32 v[70:71], v[4:5]
	v_mov_b64_e32 v[68:69], v[2:3]
	v_mov_b64_e32 v[66:67], v[0:1]
	v_mov_b64_e32 v[94:95], v[12:13]
	v_mov_b64_e32 v[92:93], v[10:11]
	v_mov_b64_e32 v[90:91], v[8:9]
	v_mov_b64_e32 v[88:89], v[6:7]
	v_mov_b64_e32 v[86:87], v[4:5]
	v_mov_b64_e32 v[84:85], v[2:3]
	v_mov_b64_e32 v[82:83], v[0:1]
	v_mov_b64_e32 v[110:111], v[12:13]
	v_mov_b64_e32 v[108:109], v[10:11]
	v_mov_b64_e32 v[106:107], v[8:9]
	v_mov_b64_e32 v[104:105], v[6:7]
	v_mov_b64_e32 v[102:103], v[4:5]
	v_mov_b64_e32 v[100:101], v[2:3]
	v_mov_b64_e32 v[98:99], v[0:1]
	v_mov_b64_e32 v[126:127], v[12:13]
	v_mov_b64_e32 v[124:125], v[10:11]
	v_mov_b64_e32 v[122:123], v[8:9]
	v_mov_b64_e32 v[120:121], v[6:7]
	v_mov_b64_e32 v[118:119], v[4:5]
	v_mov_b64_e32 v[116:117], v[2:3]
	v_mov_b64_e32 v[114:115], v[0:1]
	v_mov_b32_e32 v220, 0
	v_mov_b32_e32 v0, 0xf149f2ca
	s_mov_b32 s85, 0

.LBB0_744:
	s_and_b64 vcc, exec, s[0:1]
	s_cbranch_vccz .LBB0_739
	s_bfe_u32 s0, s5, 0x30003
	v_mov_b32_e32 v29, v193
	s_lshl_b32 s0, s0, 8
	s_ashr_i32 s3, s5, 6
	v_and_b32_e32 v0, 0xffffffc0, v29
	v_and_b32_e32 v30, 31, v29
	v_add_u32_e32 v0, s0, v0
	s_and_b32 s8, s5, 7
	s_lshl_b32 s1, s3, 3
	v_or_b32_e32 v188, v0, v30
	s_or_b32 s13, s1, s8
	v_ashrrev_i32_e32 v189, 31, v188
	v_mad_i64_i32 v[2:3], s[0:1], s13, v198, v[188:189]
	v_mov_b64_e32 v[4:5], s[40:41]
	s_movk_i32 s6, 0xc0
	v_bfe_u32 v31, v29, 5, 1
	v_mad_u64_u32 v[4:5], s[0:1], v2, s6, v[4:5]
	v_lshlrev_b32_e32 v0, 4, v31
	v_mad_i32_i24 v5, v3, s6, v5
	v_lshl_add_u64 v[26:27], v[4:5], 0, v[0:1]
	s_mov_b64 s[0:1], 0x1800
	v_lshl_add_u64 v[22:23], v[26:27], 0, s[0:1]
	s_movk_i32 s0, 0x1000
	v_add_co_u32_e32 v2, vcc, s0, v26
	s_nop 1
	v_addc_co_u32_e32 v3, vcc, 0, v27, vcc
	s_barrier
	global_load_dwordx4 v[2:5], v[2:3], off offset:2048
	s_nop 0
	global_load_dwordx4 v[6:9], v[22:23], off offset:32
	global_load_dwordx4 v[10:13], v[22:23], off offset:64
	global_load_dwordx4 v[14:17], v[22:23], off offset:96
	global_load_dwordx4 v[18:21], v[22:23], off offset:128
	s_nop 0
	global_load_dwordx4 v[22:25], v[22:23], off offset:160
	v_lshrrev_b32_e32 v29, 1, v29
	s_mov_b32 s0, 0xfffffe0
	v_and_or_b32 v29, v29, s0, v30
	s_mul_i32 s9, s13, 0x6c000
	v_add_u32_e32 v192, 0, v0
	v_readlane_b32 s0, v254, 7
	s_movk_i32 s16, 0xd0
	s_add_u32 s6, s0, s9
	v_mad_u64_u32 v[194:195], s[0:1], v29, s16, v[192:193]
	s_mul_hi_i32 s10, s13, 0x6c000
	v_readlane_b32 s0, v254, 8
	v_mov_b32_e32 v28, v193
	s_mul_hi_i32 s12, s13, 0x48000
	s_mul_i32 s13, s13, 0x48000
	s_addc_u32 s7, s0, s10
	v_readlane_b32 s0, v254, 9
	s_add_u32 s0, s0, s13
	v_readlane_b32 s1, v254, 10
	global_load_dwordx4 v[144:147], v[26:27], off
	global_load_dwordx4 v[148:151], v[26:27], off offset:32
	global_load_dwordx4 v[152:155], v[26:27], off offset:64
	global_load_dwordx4 v[156:159], v[26:27], off offset:96
	global_load_dwordx4 v[160:163], v[26:27], off offset:128
	global_load_dwordx4 v[164:167], v[26:27], off offset:160
	s_addc_u32 s1, s1, s12
	s_movk_i32 s17, 0x2000
	s_movk_i32 s11, 0x1200
	v_lshlrev_b32_e32 v190, 3, v31
	v_mul_u32_u24_e32 v191, 0xd0, v30
	v_mov_b32_e32 v215, 0xf149f2ca
	v_mov_b32_e32 v195, 0
	s_waitcnt vmcnt(11)
	ds_write_b128 v194, v[2:5] offset:47104
	s_waitcnt vmcnt(10)
	ds_write_b128 v194, v[6:9] offset:47136
	s_waitcnt vmcnt(9)
	ds_write_b128 v194, v[10:13] offset:47168
	s_waitcnt vmcnt(8)
	ds_write_b128 v194, v[14:17] offset:47200
	s_waitcnt vmcnt(7)
	ds_write_b128 v194, v[18:21] offset:47232
	s_waitcnt vmcnt(6)
	ds_write_b128 v194, v[22:25] offset:47264
	v_mov_b32_e32 v23, v193
	v_ashrrev_i32_e32 v29, 31, v28
	v_lshlrev_b32_e32 v0, 4, v28
	v_add_u32_e32 v2, 0x100, v28
	v_lshl_add_u64 v[4:5], v[28:29], 4, s[6:7]
	v_and_b32_e32 v0, 0x70, v0
	v_ashrrev_i32_e32 v14, 3, v28
	v_ashrrev_i32_e32 v3, 31, v2
	v_ashrrev_i32_e32 v16, 3, v2
	v_add_co_u32_e32 v10, vcc, s17, v4
	v_lshl_add_u64 v[12:13], s[0:1], 0, v[0:1]
	v_lshl_add_u64 v[6:7], v[2:3], 4, s[6:7]
	v_addc_co_u32_e32 v11, vcc, 0, v5, vcc
	v_mad_i64_i32 v[14:15], s[14:15], v14, s11, v[12:13]
	v_mad_i64_i32 v[18:19], s[14:15], v16, s11, v[12:13]
	global_load_dwordx4 v[2:5], v[4:5], off
	s_nop 0
	global_load_dwordx4 v[6:9], v[6:7], off
	s_nop 0
	global_load_dwordx4 v[10:13], v[10:11], off
	s_nop 0
	global_load_dwordx4 v[14:17], v[14:15], off
	s_nop 0
	global_load_dwordx4 v[18:21], v[18:19], off
	s_mov_b32 s14, 0x2aaaaaab
	v_mov_b32_e32 v22, v193
	v_mul_hi_i32 v0, v23, s14
	v_add_u32_e32 v28, 0x100, v23
	v_add_u32_e32 v29, 0x200, v23
	v_lshlrev_b32_e32 v24, 4, v23
	v_lshrrev_b32_e32 v26, 31, v0
	v_ashrrev_i32_e32 v0, 1, v0
	v_mul_hi_i32 v27, v28, s14
	v_mul_hi_i32 v32, v29, s14
	v_and_b32_e32 v24, 0x70, v24
	v_add_u32_e32 v26, v0, v26
	v_lshrrev_b32_e32 v34, 31, v27
	v_ashrrev_i32_e32 v27, 1, v27
	v_lshrrev_b32_e32 v25, 3, v23
	v_lshrrev_b32_e32 v33, 3, v28
	v_lshrrev_b32_e32 v35, 31, v32
	v_ashrrev_i32_e32 v32, 1, v32
	v_add_u32_e32 v0, 0, v24
	v_mul_lo_u32 v36, v26, 12
	v_add_u32_e32 v34, v27, v34
	v_mul_lo_u32 v37, v26, s16
	v_add_u32_e32 v32, v32, v35
	v_mad_u64_u32 v[24:25], s[14:15], v25, s91, v[0:1]
	v_mad_u64_u32 v[26:27], s[14:15], v33, s91, v[0:1]
	v_sub_u32_e32 v0, v23, v36
	v_mul_lo_u32 v23, v34, 12
	v_mul_lo_u32 v27, v32, 12
	v_sub_u32_e32 v23, v28, v23
	v_mul_lo_u32 v25, v34, s16
	v_lshlrev_b32_e32 v0, 4, v0
	v_sub_u32_e32 v27, v29, v27
	v_lshlrev_b32_e32 v23, 4, v23
	s_add_u32 s6, s6, 0x3000
	v_mul_lo_u32 v32, v32, s16
	v_add3_u32 v0, 0, v37, v0
	v_lshlrev_b32_e32 v27, 4, v27
	v_add3_u32 v23, 0, v25, v23
	s_addc_u32 s7, s7, 0
	v_add3_u32 v25, 0, v32, v27
	s_waitcnt vmcnt(4)
	ds_write_b128 v0, v[2:5]
	s_waitcnt vmcnt(3)
	ds_write_b128 v23, v[6:9]
	s_waitcnt vmcnt(2)
	ds_write_b128 v25, v[10:13]
	s_waitcnt vmcnt(1)
	ds_write_b128 v24, v[14:17] offset:13312
	s_waitcnt vmcnt(0)
	ds_write_b128 v26, v[18:21] offset:13312
	v_mov_b32_e32 v204, v0
	v_mov_b32_e32 v205, v23
	v_mov_b32_e32 v209, v25
	v_mov_b32_e32 v212, v24
	v_mov_b32_e32 v235, v26
	v_mov_b32_e32 v14, v1
	v_ashrrev_i32_e32 v23, 31, v22
	v_add_u32_e32 v2, 0x100, v22
	v_lshlrev_b32_e32 v0, 4, v22
	v_lshl_add_u64 v[4:5], v[22:23], 4, s[6:7]
	v_ashrrev_i32_e32 v3, 31, v2
	v_and_b32_e32 v0, 0x70, v0
	v_add_co_u32_e32 v6, vcc, s17, v4
	v_ashrrev_i32_e32 v10, 3, v22
	v_ashrrev_i32_e32 v11, 3, v2
	v_lshl_add_u64 v[2:3], v[2:3], 4, s[6:7]
	v_addc_co_u32_e32 v7, vcc, 0, v5, vcc
	v_lshl_add_u64 v[8:9], s[0:1], 0, v[0:1]
	global_load_dwordx4 v[168:171], v[4:5], off
	global_load_dwordx4 v[172:175], v[2:3], off
	v_mad_i64_i32 v[2:3], s[0:1], v10, s11, v[8:9]
	v_mad_i64_i32 v[4:5], s[0:1], v11, s11, v[8:9]
	global_load_dwordx4 v[176:179], v[6:7], off
	global_load_dwordx4 v[180:183], v[2:3], off offset:128
	global_load_dwordx4 v[184:187], v[4:5], off offset:128
	v_and_b32_e32 v2, 64, v200
	v_xor_b32_e32 v0, 32, v200
	v_add_u32_e32 v2, 64, v2
	v_cmp_lt_i32_e32 vcc, v0, v2
	v_readlane_b32 s0, v255, 23
	s_add_u32 s9, s0, s9
	v_cndmask_b32_e32 v0, v200, v0, vcc
	v_readlane_b32 s0, v255, 24
	v_lshlrev_b32_e32 v189, 2, v0
	v_sub_u32_e32 v0, v192, v190
	v_mul_u32_u24_e32 v2, 0x48, v30
	s_addc_u32 s10, s0, s10
	v_readlane_b32 s0, v255, 25
	v_mov_b32_e32 v15, v1
	v_lshl_add_u32 v214, v2, 1, v0
	s_add_u32 s0, s0, s13
	v_readlane_b32 s1, v255, 26
	v_mov_b32_e32 v0, v1
	v_mov_b32_e32 v2, v1
	v_mov_b32_e32 v3, v1
	v_mov_b32_e32 v4, v1
	v_mov_b32_e32 v5, v1
	v_mov_b32_e32 v6, v1
	v_mov_b32_e32 v7, v1
	v_mov_b32_e32 v8, v1
	v_mov_b32_e32 v9, v1
	v_mov_b32_e32 v10, v1
	v_mov_b32_e32 v11, v1
	v_mov_b32_e32 v12, v1
	v_mov_b32_e32 v13, v1
	v_mov_b64_e32 v[30:31], v[14:15]
	v_mov_b64_e32 v[46:47], v[14:15]
	v_mov_b64_e32 v[62:63], v[14:15]
	v_mov_b64_e32 v[78:79], v[14:15]
	s_movk_i32 s16, 0x2000
	s_mov_b32 s11, 0
	s_addc_u32 s1, s1, s12
	s_mov_b64 s[6:7], 0
	v_mov_b64_e32 v[28:29], v[12:13]
	v_mov_b64_e32 v[26:27], v[10:11]
	v_mov_b64_e32 v[24:25], v[8:9]
	v_mov_b64_e32 v[22:23], v[6:7]
	v_mov_b64_e32 v[20:21], v[4:5]
	v_mov_b64_e32 v[18:19], v[2:3]
	v_mov_b64_e32 v[16:17], v[0:1]
	v_mov_b64_e32 v[44:45], v[12:13]
	v_mov_b64_e32 v[42:43], v[10:11]
	v_mov_b64_e32 v[40:41], v[8:9]
	v_mov_b64_e32 v[38:39], v[6:7]
	v_mov_b64_e32 v[36:37], v[4:5]
	v_mov_b64_e32 v[34:35], v[2:3]
	v_mov_b64_e32 v[32:33], v[0:1]
	v_mov_b64_e32 v[60:61], v[12:13]
	v_mov_b64_e32 v[58:59], v[10:11]
	v_mov_b64_e32 v[56:57], v[8:9]
	v_mov_b64_e32 v[54:55], v[6:7]
	v_mov_b64_e32 v[52:53], v[4:5]
	v_mov_b64_e32 v[50:51], v[2:3]
	v_mov_b64_e32 v[48:49], v[0:1]
	v_mov_b64_e32 v[76:77], v[12:13]
	v_mov_b64_e32 v[74:75], v[10:11]
	v_mov_b64_e32 v[72:73], v[8:9]
	v_mov_b64_e32 v[70:71], v[6:7]
	v_mov_b64_e32 v[68:69], v[4:5]
	v_mov_b64_e32 v[66:67], v[2:3]
	v_mov_b64_e32 v[64:65], v[0:1]
	v_mov_b32_e32 v0, 0
	v_mov_b32_e32 v14, 0xf149f2ca
	s_waitcnt lgkmcnt(0)
	s_barrier
